# v93: v92 + differential-head epilogue: gate loads paired into dwordx4, output-norm gains from an LDS copy, vmcnt(0) moved behind the hand-off
# speedup vs baseline: 1.0181x; 1.0028x over previous
; #define LAS __attribute__((address_space(3)))
; template <int MODE>
; __device__ __forceinline__ void attn_unit(const Params& P, LAS unsigned char* lds, const int b, const int h, const int qb) {
;     ...
;             for (int a = 0; a < 4; ++a) { const int d0 = 32 * d + 8 * a + 4 * hh; zv[d][a] = *(const u32x2*)(zp + d0); if (!FOX) gv[d][a] = *(const f32x4*)(P.in[I_DON] + d0); }
; __device__ __forceinline__ void attn_phase(const Params& P, LAS unsigned char* lds) {
;     int tid_ = threadIdx.x; asm volatile("" : "+v"(tid_)); const int tid = tid_;
;     unsigned* ctr = (unsigned*)(P.ws + WS_CTL);
;     LAS int* misc = (LAS int*)(lds + AL_MISC);
;     const int xq = (int)(__builtin_amdgcn_s_getreg((3 << 11) | 20) & 7u);
;     const bool bounded = ((const float*)(P.ws + WS_TAB))[TAB_DBOUND] <= 60.0f;
;     for (;;) {
.LBB0_418:
	v_writelane_b32 v255, s88, 3
	s_nop 1
	v_writelane_b32 v255, s89, 4
	v_writelane_b32 v255, s94, 5
	s_nop 1
	v_writelane_b32 v255, s95, 6
	s_or_b64 exec, exec, s[4:5]
	s_waitcnt lgkmcnt(0)
	v_mov_b32_e32 v0, v178
	v_mov_b32_e32 v1, 0x2000
	s_barrier
	s_getreg_b32 s3, hwreg(HW_REG_XCC_ID, 0, 4)
	global_load_dword v2, v1, s[52:53] offset:136
	global_load_dword v3, v1, s[52:53] offset:132
	v_and_b32_e32 v236, 0x7f, v178
	v_lshlrev_b32_e32 v236, 2, v236
	global_load_dword v237, v236, s[46:47]
	s_lshr_b32 s72, s75, 16
	s_and_b32 s0, s75, 0xffff
	s_add_u32 s78, s52, 0x18324000
	s_addc_u32 s79, s53, 0
	s_add_u32 s80, s52, 0x1c324000
	s_addc_u32 s81, s53, 0
	s_add_u32 s82, s52, 0x124000
	s_addc_u32 s83, s53, 0
	s_add_u32 s60, s52, 0x2084
	s_addc_u32 s61, s53, 0
	s_add_u32 s84, s52, 0x20324000
	s_addc_u32 s85, s53, 0
	s_add_u32 s86, s52, 0x24324000
	s_addc_u32 s87, s53, 0
	s_add_u32 s88, s52, 0x28324000
	s_addc_u32 s89, s53, 0
	s_add_u32 s90, s52, 0x2c324000
	s_addc_u32 s91, s53, 0
	s_add_u32 s92, s52, 0x30324000
	s_addc_u32 s93, s53, 0
	s_mov_b32 s6, 0x22000
	s_add_u32 s62, s52, 0x2080
	s_mov_b32 s1, 0x42700000
	s_addc_u32 s63, s53, 0
	s_add_i32 s95, s6, 0x100
	s_mov_b32 s13, 0
	v_mov_b32_e32 v1, 0
	s_mov_b64 s[28:29], 0x2000
	s_movk_i32 s73, 0x4000
	s_movk_i32 s75, 0x81
	s_mov_b32 s76, 0x22100
	s_mov_b64 s[30:31], 0x4000
	s_mov_b64 s[36:37], 0x6000
	s_mov_b64 s[42:43], 0x28330000
	s_mov_b64 s[44:45], 0x28332000
	s_mov_b64 s[48:49], 0x2c330000
	s_mov_b64 s[50:51], 0x2c332000
	v_mov_b32_e32 v230, 0x358637bd
	v_mbcnt_hi_u32_b32 v179, -1, v173
	v_mov_b32_e32 v231, 0xff800000
	v_mov_b32_e32 v232, 0x100
	v_mad_u32_u24 v233, v172, s0, v254
	v_cmp_eq_u32_e64 s[4:5], 0, v0
	s_lshl_b32 s94, s0, 8
	v_mov_b32_e32 v234, s95
	v_mov_b32_e32 v235, 0x80
	s_waitcnt vmcnt(0)
	v_cmp_ge_f32_e64 s[6:7], s1, v2
	v_mov_b32_e32 v4, 0x42f00000
	v_cmp_ge_f32_e64 s[100:101], v4, v3
	v_readfirstlane_b32 s0, v3
	s_nop 3
	v_writelane_b32 v255, s0, 8
	v_add_u32_e32 v236, 0x22800, v236
	ds_write_b32 v236, v237
	s_branch .LBB0_421

; #define LAS __attribute__((address_space(3)))
; __device__ __forceinline__ float silu_f(float z) { return z * __builtin_amdgcn_rcpf(1.0f + __builtin_amdgcn_exp2f(-LOG2E * z)); }
; __device__ __forceinline__ float bf_lo(unsigned v) { return __uint_as_float(v << 16); }
; __device__ __forceinline__ float bf_hi(unsigned v) { return __uint_as_float(v & 0xffff0000u); }
; template <int MODE>
; __device__ __forceinline__ void attn_unit(const Params& P, LAS unsigned char* lds, const int b, const int h, const int qb) {
;     ...
;     bf16_t* mix = (bf16_t*)(P.ws + WS_MIX) + (tokbase + q) * DM + colO;
;     const bf16_t* zp = Zb + (size_t)q * RS;
;     const float inv1 = 1.0f / (l1 + __shfl_xor(l1, 32));
;     u32x2 zv[4][4]; f32x4 gv[4][4];
;     if (FOX || mp == 0) {
; #pragma unroll
;         for (int d = 0; d < 4; ++d)
; #pragma unroll
;             for (int a = 0; a < 4; ++a) { const int d0 = 32 * d + 8 * a + 4 * hh; zv[d][a] = *(const u32x2*)(zp + d0); if (!FOX) gv[d][a] = *(const f32x4*)(P.in[I_DON] + d0); }
;     }
;     asm volatile("" ::: "memory");
;     if (FOX) {
; #pragma unroll
;         for (int d = 0; d < 4; ++d)
; #pragma unroll
;             for (int a = 0; a < 4; ++a) { const int d0 = 32 * d + 8 * a + 4 * hh; const u32x2 z2 = zv[d][a];
;                 const float o0 = O[d][4 * a] * inv1 * silu_f(bf_lo(z2.x)), o1 = O[d][4 * a + 1] * inv1 * silu_f(bf_hi(z2.x));
;                 const float o2 = O[d][4 * a + 2] * inv1 * silu_f(bf_lo(z2.y)), o3 = O[d][4 * a + 3] * inv1 * silu_f(bf_hi(z2.y));
;                 u32x2 ov; ov.x = cvt_pk_bf16(o0, o1); ov.y = cvt_pk_bf16(o2, o3); *(u32x2*)(mix + d0) = ov; }
;         __syncthreads();
;     } else {
;         __syncthreads();
;         LAS float* xb = (LAS float*)lds;
;         if (mp == 1) {
; #pragma unroll
;             for (int d = 0; d < 4; ++d)
; #pragma unroll
;                 for (int i = 0; i < 16; ++i) xb[(((w & 3) * 4 + d) * 16 + i) * 64 + lane] = O[d][i] * inv1;
;         }
;         __syncthreads();
.LBB0_490:
	v_and_b32_e32 v2, 64, v179
	v_xor_b32_e32 v0, 32, v179
	v_add_u32_e32 v2, 64, v2
	v_cmp_lt_i32_e32 vcc, v0, v2
	s_cmpk_lt_u32 s58, 0x100
	s_cselect_b64 s[68:69], -1, 0
	v_cndmask_b32_e32 v0, v179, v0, vcc
	v_lshlrev_b32_e32 v228, 2, v0
	ds_bpermute_b32 v164, v228, v163
	s_cmpk_gt_u32 s58, 0xff
	s_cbranch_scc1 .LBB0_492
	s_add_u32 s22, s92, s66
	s_addc_u32 s23, s93, s67
	v_lshlrev_b32_e32 v0, 1, v149
	v_lshl_add_u64 v[2:3], s[22:23], 0, v[0:1]
	v_mov_b32_e32 v149, v1
	v_lshl_add_u64 v[2:3], v[2:3], 0, v[148:149]
	v_mad_i32_i24 v252, v148, -3, 16
	v_ashrrev_i32_e32 v253, 31, v252
	v_lshl_add_u64 v[252:253], v[2:3], 0, v[252:253]
	global_load_dwordx4 v[240:243], v[252:253], off
	global_load_dwordx4 v[244:247], v[252:253], off offset:32
	global_load_dwordx4 v[154:157], v[252:253], off offset:64
	global_load_dwordx4 v[248:251], v[252:253], off offset:96
	global_load_dwordx4 v[142:145], v[252:253], off offset:128
	global_load_dwordx4 v[138:141], v[252:253], off offset:160
	global_load_dwordx4 v[134:137], v[252:253], off offset:192
	global_load_dwordx4 v[184:187], v[252:253], off offset:224
	v_add_u32_e32 v229, 0x22800, v150
	ds_read_b128 v[128:131], v229
	ds_read_b128 v[124:127], v229 offset:32
	ds_read_b128 v[120:123], v229 offset:64
	ds_read_b128 v[116:119], v229 offset:96
	ds_read_b128 v[112:115], v229 offset:128
	ds_read_b128 v[108:111], v229 offset:160
	ds_read_b128 v[104:107], v229 offset:192
	ds_read_b128 v[100:103], v229 offset:224
	ds_read_b128 v[96:99], v229 offset:256
	ds_read_b128 v[92:95], v229 offset:288
	ds_read_b128 v[88:91], v229 offset:320
	ds_read_b128 v[84:87], v229 offset:352
	ds_read_b128 v[80:83], v229 offset:384
	ds_read_b128 v[10:13], v229 offset:416
	ds_read_b128 v[6:9], v229 offset:448
	ds_read_b128 v[2:5], v229 offset:480
.LBB0_492:
	s_waitcnt lgkmcnt(0)
	v_add_f32_e32 v0, v163, v164
	v_div_scale_f32 v149, s[22:23], v0, v0, 1.0
	v_rcp_f32_e32 v150, v149
	v_div_scale_f32 v163, vcc, 1.0, v0, 1.0
	v_fma_f32 v164, -v149, v150, 1.0
	v_fmac_f32_e32 v150, v164, v150
	v_mul_f32_e32 v164, v163, v150
	v_fma_f32 v165, -v149, v164, v163
	v_fmac_f32_e32 v164, v165, v150
	v_fma_f32 v149, -v149, v164, v163
	v_div_fmas_f32 v149, v149, v150, v164
	v_div_fixup_f32 v150, v149, v0, 1.0
	s_cmp_lg_u32 s1, 1
	s_movk_i32 s75, 0x81
	s_barrier
	s_cbranch_scc1 .LBB0_494
	s_lshl_b32 s0, s0, 14
	s_addk_i32 s0, 0x100
	v_mul_f32_e32 v0, v64, v150
	v_lshl_add_u32 v149, v151, 2, s0
	v_mul_f32_e32 v163, v65, v150
	ds_write2st64_b32 v149, v0, v163 offset1:1
	v_mul_f32_e32 v0, v66, v150
	v_mul_f32_e32 v163, v67, v150
	ds_write2st64_b32 v149, v0, v163 offset0:2 offset1:3
	v_mul_f32_e32 v0, v68, v150
	v_mul_f32_e32 v163, v69, v150
	ds_write2st64_b32 v149, v0, v163 offset0:4 offset1:5
	v_mul_f32_e32 v0, v70, v150
	v_mul_f32_e32 v163, v71, v150
	ds_write2st64_b32 v149, v0, v163 offset0:6 offset1:7
	v_mul_f32_e32 v0, v72, v150
	v_mul_f32_e32 v163, v73, v150
	ds_write2st64_b32 v149, v0, v163 offset0:8 offset1:9
	v_mul_f32_e32 v0, v74, v150
	v_mul_f32_e32 v163, v75, v150
	ds_write2st64_b32 v149, v0, v163 offset0:10 offset1:11
	v_mul_f32_e32 v0, v76, v150
	v_mul_f32_e32 v163, v77, v150
	ds_write2st64_b32 v149, v0, v163 offset0:12 offset1:13
	v_mul_f32_e32 v0, v78, v150
	v_mul_f32_e32 v163, v79, v150
	ds_write2st64_b32 v149, v0, v163 offset0:14 offset1:15
	v_mul_f32_e32 v0, v48, v150
	v_mul_f32_e32 v163, v49, v150
	ds_write2st64_b32 v149, v0, v163 offset0:16 offset1:17
	v_mul_f32_e32 v0, v50, v150
	v_mul_f32_e32 v163, v51, v150
	ds_write2st64_b32 v149, v0, v163 offset0:18 offset1:19
	v_mul_f32_e32 v0, v52, v150
	v_mul_f32_e32 v163, v53, v150
	ds_write2st64_b32 v149, v0, v163 offset0:20 offset1:21
	v_mul_f32_e32 v0, v54, v150
	v_mul_f32_e32 v163, v55, v150
	ds_write2st64_b32 v149, v0, v163 offset0:22 offset1:23
	v_mul_f32_e32 v0, v56, v150
	v_mul_f32_e32 v163, v57, v150
	ds_write2st64_b32 v149, v0, v163 offset0:24 offset1:25
	v_mul_f32_e32 v0, v58, v150
	v_mul_f32_e32 v163, v59, v150
	ds_write2st64_b32 v149, v0, v163 offset0:26 offset1:27
	v_mul_f32_e32 v0, v60, v150
	v_mul_f32_e32 v163, v61, v150
	ds_write2st64_b32 v149, v0, v163 offset0:28 offset1:29
	v_mul_f32_e32 v0, v62, v150
	v_mul_f32_e32 v163, v63, v150
	ds_write2st64_b32 v149, v0, v163 offset0:30 offset1:31
	v_mul_f32_e32 v0, v32, v150
	v_mul_f32_e32 v163, v33, v150
	ds_write2st64_b32 v149, v0, v163 offset0:32 offset1:33
	v_mul_f32_e32 v0, v34, v150
	v_mul_f32_e32 v163, v35, v150
	ds_write2st64_b32 v149, v0, v163 offset0:34 offset1:35
	v_mul_f32_e32 v0, v36, v150
	v_mul_f32_e32 v163, v37, v150
	ds_write2st64_b32 v149, v0, v163 offset0:36 offset1:37
	v_mul_f32_e32 v0, v38, v150
	v_mul_f32_e32 v163, v39, v150
	ds_write2st64_b32 v149, v0, v163 offset0:38 offset1:39
	v_mul_f32_e32 v0, v40, v150
	v_mul_f32_e32 v163, v41, v150
	ds_write2st64_b32 v149, v0, v163 offset0:40 offset1:41
	v_mul_f32_e32 v0, v42, v150
	v_mul_f32_e32 v163, v43, v150
	ds_write2st64_b32 v149, v0, v163 offset0:42 offset1:43
	v_mul_f32_e32 v0, v44, v150
	v_mul_f32_e32 v163, v45, v150
	ds_write2st64_b32 v149, v0, v163 offset0:44 offset1:45
	v_mul_f32_e32 v0, v46, v150
	v_mul_f32_e32 v163, v47, v150
	ds_write2st64_b32 v149, v0, v163 offset0:46 offset1:47
	v_mul_f32_e32 v0, v16, v150
	v_mul_f32_e32 v163, v17, v150
	ds_write2st64_b32 v149, v0, v163 offset0:48 offset1:49
	v_mul_f32_e32 v0, v18, v150
	v_mul_f32_e32 v163, v19, v150
	ds_write2st64_b32 v149, v0, v163 offset0:50 offset1:51
	v_mul_f32_e32 v0, v20, v150
	v_mul_f32_e32 v163, v21, v150
	ds_write2st64_b32 v149, v0, v163 offset0:52 offset1:53
	v_mul_f32_e32 v0, v22, v150
	v_mul_f32_e32 v163, v23, v150
	ds_write2st64_b32 v149, v0, v163 offset0:54 offset1:55
	v_mul_f32_e32 v0, v24, v150
	v_mul_f32_e32 v163, v25, v150
	ds_write2st64_b32 v149, v0, v163 offset0:56 offset1:57
	v_mul_f32_e32 v0, v26, v150
	v_mul_f32_e32 v163, v27, v150
	ds_write2st64_b32 v149, v0, v163 offset0:58 offset1:59
	v_mul_f32_e32 v0, v28, v150
	v_mul_f32_e32 v163, v29, v150
	ds_write2st64_b32 v149, v0, v163 offset0:60 offset1:61
	v_mul_f32_e32 v0, v30, v150
	v_mul_f32_e32 v163, v31, v150
	ds_write2st64_b32 v149, v0, v163 offset0:62 offset1:63
; __device__ __forceinline__ float silu_f(float z) { return z * __builtin_amdgcn_rcpf(1.0f + __builtin_amdgcn_exp2f(-LOG2E * z)); }
; __device__ __forceinline__ float bf_lo(unsigned v) { return __uint_as_float(v << 16); }
; __device__ __forceinline__ float bf_hi(unsigned v) { return __uint_as_float(v & 0xffff0000u); }
; template <int MODE>
; __device__ __forceinline__ void attn_unit(const Params& P, LAS unsigned char* lds, const int b, const int h, const int qb) {
;     ...
;         if (mp == 0) {
;             const float lam = tab[TAB_LAM]; float ss = 0.f;
; #pragma unroll
;             for (int d = 0; d < 4; ++d)
; #pragma unroll
;                 for (int i = 0; i < 16; ++i) { const float o = O[d][i] * inv1 - lam * xb[((w * 4 + d) * 16 + i) * 64 + lane]; O[d][i] = o; ss += o * o; }
;     ...
;                 for (int a = 0; a < 4; ++a) { const int d0 = 32 * d + 8 * a + 4 * hh; const u32x2 z2 = zv[d][a]; const f32x4 g = gv[d][a];
;                     const float o0 = O[d][4 * a] * rstd * g[0] * silu_f(bf_lo(z2.x)), o1 = O[d][4 * a + 1] * rstd * g[1] * silu_f(bf_hi(z2.x));
;                     const float o2 = O[d][4 * a + 2] * rstd * g[2] * silu_f(bf_lo(z2.y)), o3 = O[d][4 * a + 3] * rstd * g[3] * silu_f(bf_hi(z2.y));
.LBB0_494:
	s_andn2_b64 vcc, exec, s[68:69]
	s_waitcnt lgkmcnt(0)
	s_barrier
	s_cbranch_vccnz .LBB0_496
	s_waitcnt vmcnt(0)
	v_permlane32_swap_b32 v240, v242
	v_permlane32_swap_b32 v241, v243
	v_mov_b32_e32 v170, v240
	v_mov_b32_e32 v171, v241
	v_mov_b32_e32 v160, v242
	v_mov_b32_e32 v161, v243
	v_permlane32_swap_b32 v244, v246
	v_permlane32_swap_b32 v245, v247
	v_mov_b32_e32 v158, v244
	v_mov_b32_e32 v159, v245
	v_mov_b32_e32 v168, v246
	v_mov_b32_e32 v169, v247
	v_permlane32_swap_b32 v154, v156
	v_permlane32_swap_b32 v155, v157
	v_permlane32_swap_b32 v248, v250
	v_permlane32_swap_b32 v249, v251
	v_mov_b32_e32 v146, v248
	v_mov_b32_e32 v147, v249
	v_mov_b32_e32 v152, v250
	v_mov_b32_e32 v153, v251
	v_permlane32_swap_b32 v142, v144
	v_permlane32_swap_b32 v143, v145
	v_permlane32_swap_b32 v138, v140
	v_permlane32_swap_b32 v139, v141
	v_permlane32_swap_b32 v134, v136
	v_permlane32_swap_b32 v135, v137
	v_permlane32_swap_b32 v184, v186
	v_permlane32_swap_b32 v185, v187
	v_mov_b32_e32 v14, v184
	v_mov_b32_e32 v15, v185
	v_mov_b32_e32 v132, v186
	v_mov_b32_e32 v133, v187
	global_load_dword v172, v1, s[62:63]
	v_lshlrev_b32_e32 v182, 16, v161
	v_lshlrev_b32_e32 v0, 12, v162
	v_mul_f32_e32 v162, 0xbfb8aa3b, v182
	s_lshl_b32 s0, s11, 14
	v_exp_f32_e32 v173, v162
	s_lshl_b64 s[68:69], s[12:13], 25
	v_lshlrev_b32_e32 v180, 16, v160
	v_and_b32_e32 v181, 0xffff0000, v160
	v_and_b32_e32 v183, 0xffff0000, v161
	v_lshl_add_u64 v[160:161], s[52:53], 0, v[0:1]
	s_addk_i32 s0, 0x100
	s_lshl_b32 s66, s96, 8
	s_mov_b32 s67, s13
	v_mul_f32_e32 v163, 0xbfb8aa3b, v183
	v_lshl_add_u64 v[160:161], v[160:161], 0, s[68:69]
	v_lshl_add_u32 v151, v151, 2, s0
	v_exp_f32_e32 v229, v163
	v_lshl_add_u64 v[226:227], v[160:161], 0, s[66:67]
	ds_read2st64_b32 v[160:161], v151 offset1:1
	ds_read2st64_b32 v[162:163], v151 offset0:2 offset1:3
	ds_read2st64_b32 v[164:165], v151 offset0:4 offset1:5
	ds_read2st64_b32 v[166:167], v151 offset0:6 offset1:7
	ds_read2st64_b32 v[174:175], v151 offset0:8 offset1:9
	ds_read2st64_b32 v[176:177], v151 offset0:10 offset1:11
	ds_read2st64_b32 v[192:193], v151 offset0:12 offset1:13
	ds_read2st64_b32 v[194:195], v151 offset0:14 offset1:15
	ds_read2st64_b32 v[222:223], v151 offset0:16 offset1:17
	ds_read2st64_b32 v[224:225], v151 offset0:18 offset1:19
	ds_read2st64_b32 v[210:211], v151 offset0:20 offset1:21
	ds_read2st64_b32 v[212:213], v151 offset0:22 offset1:23
	ds_read2st64_b32 v[202:203], v151 offset0:24 offset1:25
	ds_read2st64_b32 v[204:205], v151 offset0:26 offset1:27
	ds_read2st64_b32 v[188:189], v151 offset0:28 offset1:29
	ds_read2st64_b32 v[190:191], v151 offset0:30 offset1:31
	ds_read2st64_b32 v[218:219], v151 offset0:32 offset1:33
	ds_read2st64_b32 v[220:221], v151 offset0:34 offset1:35
	ds_read2st64_b32 v[214:215], v151 offset0:36 offset1:37
	ds_read2st64_b32 v[216:217], v151 offset0:38 offset1:39
	ds_read2st64_b32 v[206:207], v151 offset0:40 offset1:41
	ds_read2st64_b32 v[208:209], v151 offset0:42 offset1:43
	ds_read2st64_b32 v[198:199], v151 offset0:44 offset1:45
	ds_read2st64_b32 v[200:201], v151 offset0:46 offset1:47
	ds_read2st64_b32 v[184:185], v151 offset0:48 offset1:49
	ds_read2st64_b32 v[186:187], v151 offset0:50 offset1:51
	v_mul_f32_e32 v0, 0xbfb8aa3b, v180
	v_mul_f32_e32 v149, 0xbfb8aa3b, v181
	v_exp_f32_e32 v0, v0
	v_exp_f32_e32 v149, v149
	s_mov_b64 s[0:1], 0x4324800
	v_add_f32_e32 v0, 1.0, v0
	s_waitcnt vmcnt(0) lgkmcnt(14)
	v_pk_mul_f32 v[162:163], v[172:173], v[162:163] op_sel_hi:[0,1]
	v_pk_mul_f32 v[160:161], v[172:173], v[160:161] op_sel_hi:[0,1]
	v_pk_mul_f32 v[196:197], v[172:173], v[166:167] op_sel_hi:[0,1]
	v_pk_mul_f32 v[236:237], v[172:173], v[164:165] op_sel_hi:[0,1]
	v_pk_mul_f32 v[176:177], v[172:173], v[176:177] op_sel_hi:[0,1]
	v_pk_mul_f32 v[174:175], v[172:173], v[174:175] op_sel_hi:[0,1]
	v_pk_mul_f32 v[194:195], v[172:173], v[194:195] op_sel_hi:[0,1]
	v_pk_mul_f32 v[192:193], v[172:173], v[192:193] op_sel_hi:[0,1]
	v_pk_fma_f32 v[164:165], v[66:67], v[150:151], v[162:163] op_sel_hi:[1,0,1] neg_lo:[0,0,1] neg_hi:[0,0,1]
	v_pk_fma_f32 v[166:167], v[64:65], v[150:151], v[160:161] op_sel_hi:[1,0,1] neg_lo:[0,0,1] neg_hi:[0,0,1]
	v_pk_fma_f32 v[160:161], v[70:71], v[150:151], v[196:197] op_sel_hi:[1,0,1] neg_lo:[0,0,1] neg_hi:[0,0,1]
	v_pk_fma_f32 v[162:163], v[68:69], v[150:151], v[236:237] op_sel_hi:[1,0,1] neg_lo:[0,0,1] neg_hi:[0,0,1]
	v_pk_fma_f32 v[68:69], v[74:75], v[150:151], v[176:177] op_sel_hi:[1,0,1] neg_lo:[0,0,1] neg_hi:[0,0,1]
	v_pk_fma_f32 v[70:71], v[72:73], v[150:151], v[174:175] op_sel_hi:[1,0,1] neg_lo:[0,0,1] neg_hi:[0,0,1]
	v_pk_fma_f32 v[64:65], v[78:79], v[150:151], v[194:195] op_sel_hi:[1,0,1] neg_lo:[0,0,1] neg_hi:[0,0,1]
	v_pk_fma_f32 v[66:67], v[76:77], v[150:151], v[192:193] op_sel_hi:[1,0,1] neg_lo:[0,0,1] neg_hi:[0,0,1]
	ds_read2st64_b32 v[194:195], v151 offset0:52 offset1:53
	ds_read2st64_b32 v[196:197], v151 offset0:54 offset1:55
	ds_read2st64_b32 v[192:193], v151 offset0:56 offset1:57
	ds_read2st64_b32 v[72:73], v151 offset0:58 offset1:59
	ds_read2st64_b32 v[74:75], v151 offset0:60 offset1:61
	ds_read2st64_b32 v[76:77], v151 offset0:62 offset1:63
	v_add_f32_e32 v79, 1.0, v149
	v_add_f32_e32 v149, 1.0, v173
	v_rcp_f32_e32 v78, v0
	s_waitcnt lgkmcnt(2)
	v_pk_mul_f32 v[72:73], v[172:173], v[72:73] op_sel_hi:[0,1]
	s_waitcnt lgkmcnt(0)
; __device__ __forceinline__ float silu_f(float z) { return z * __builtin_amdgcn_rcpf(1.0f + __builtin_amdgcn_exp2f(-LOG2E * z)); }
; __device__ __forceinline__ float bf_lo(unsigned v) { return __uint_as_float(v << 16); }
; __device__ __forceinline__ float bf_hi(unsigned v) { return __uint_as_float(v & 0xffff0000u); }
; template <int MODE>
; __device__ __forceinline__ void attn_unit(const Params& P, LAS unsigned char* lds, const int b, const int h, const int qb) {
;     ...
;             for (int d = 0; d < 4; ++d)
; #pragma unroll
;                 for (int i = 0; i < 16; ++i) { const float o = O[d][i] * inv1 - lam * xb[((w * 4 + d) * 16 + i) * 64 + lane]; O[d][i] = o; ss += o * o; }
;             ss += __shfl_xor(ss, 32);
;             const float rstd = 0.8f * __builtin_amdgcn_rsqf(ss * (1.0f / 128.0f) + 1e-6f);
; #pragma unroll
;             for (int d = 0; d < 4; ++d)
; #pragma unroll
;                 for (int a = 0; a < 4; ++a) { const int d0 = 32 * d + 8 * a + 4 * hh; const u32x2 z2 = zv[d][a]; const f32x4 g = gv[d][a];
;                     const float o0 = O[d][4 * a] * rstd * g[0] * silu_f(bf_lo(z2.x)), o1 = O[d][4 * a + 1] * rstd * g[1] * silu_f(bf_hi(z2.x));
;                     const float o2 = O[d][4 * a + 2] * rstd * g[2] * silu_f(bf_lo(z2.y)), o3 = O[d][4 * a + 3] * rstd * g[3] * silu_f(bf_hi(z2.y));
	v_pk_mul_f32 v[76:77], v[172:173], v[76:77] op_sel_hi:[0,1]
	v_add_f32_e32 v0, 1.0, v229
	v_pk_fma_f32 v[72:73], v[26:27], v[150:151], v[72:73] op_sel_hi:[1,0,1] neg_lo:[0,0,1] neg_hi:[0,0,1]
	v_pk_fma_f32 v[26:27], v[30:31], v[150:151], v[76:77] op_sel_hi:[1,0,1] neg_lo:[0,0,1] neg_hi:[0,0,1]
	v_rcp_f32_e32 v30, v149
	v_rcp_f32_e32 v31, v0
	v_pk_mul_f32 v[74:75], v[172:173], v[74:75] op_sel_hi:[0,1]
	v_pk_fma_f32 v[28:29], v[28:29], v[150:151], v[74:75] op_sel_hi:[1,0,1] neg_lo:[0,0,1] neg_hi:[0,0,1]
	v_mov_b32_e32 v149, v1
	v_pk_mul_f32 v[76:77], v[30:31], v[182:183]
	v_pk_mul_f32 v[30:31], v[172:173], v[224:225] op_sel_hi:[0,1]
	v_pk_fma_f32 v[50:51], v[50:51], v[150:151], v[30:31] op_sel_hi:[1,0,1] neg_lo:[0,0,1] neg_hi:[0,0,1]
	v_pk_mul_f32 v[30:31], v[172:173], v[222:223] op_sel_hi:[0,1]
	v_pk_fma_f32 v[48:49], v[48:49], v[150:151], v[30:31] op_sel_hi:[1,0,1] neg_lo:[0,0,1] neg_hi:[0,0,1]
	v_pk_mul_f32 v[30:31], v[172:173], v[212:213] op_sel_hi:[0,1]
	v_pk_fma_f32 v[54:55], v[54:55], v[150:151], v[30:31] op_sel_hi:[1,0,1] neg_lo:[0,0,1] neg_hi:[0,0,1]
	v_pk_mul_f32 v[30:31], v[172:173], v[210:211] op_sel_hi:[0,1]
	v_pk_fma_f32 v[52:53], v[52:53], v[150:151], v[30:31] op_sel_hi:[1,0,1] neg_lo:[0,0,1] neg_hi:[0,0,1]
	v_pk_mul_f32 v[30:31], v[172:173], v[204:205] op_sel_hi:[0,1]
	v_pk_fma_f32 v[58:59], v[58:59], v[150:151], v[30:31] op_sel_hi:[1,0,1] neg_lo:[0,0,1] neg_hi:[0,0,1]
	v_pk_mul_f32 v[30:31], v[172:173], v[202:203] op_sel_hi:[0,1]
	v_pk_fma_f32 v[56:57], v[56:57], v[150:151], v[30:31] op_sel_hi:[1,0,1] neg_lo:[0,0,1] neg_hi:[0,0,1]
	v_pk_mul_f32 v[30:31], v[172:173], v[190:191] op_sel_hi:[0,1]
	v_pk_fma_f32 v[62:63], v[62:63], v[150:151], v[30:31] op_sel_hi:[1,0,1] neg_lo:[0,0,1] neg_hi:[0,0,1]
	v_pk_mul_f32 v[30:31], v[172:173], v[188:189] op_sel_hi:[0,1]
	v_lshlrev_b32_e32 v188, 16, v170
	v_and_b32_e32 v189, 0xffff0000, v170
	v_mul_f32_e32 v0, 0xbfb8aa3b, v188
	v_pk_fma_f32 v[60:61], v[60:61], v[150:151], v[30:31] op_sel_hi:[1,0,1] neg_lo:[0,0,1] neg_hi:[0,0,1]
	v_exp_f32_e32 v0, v0
	v_mul_f32_e32 v151, 0xbfb8aa3b, v189
	v_exp_f32_e32 v151, v151
	v_lshlrev_b32_e32 v210, 16, v171
	v_add_f32_e32 v0, 1.0, v0
	v_rcp_f32_e32 v190, v0
	v_add_f32_e32 v0, 1.0, v151
	v_rcp_f32_e32 v191, v0
	v_and_b32_e32 v211, 0xffff0000, v171
	v_mul_f32_e32 v0, 0xbfb8aa3b, v210
	v_exp_f32_e32 v0, v0
	v_mul_f32_e32 v151, 0xbfb8aa3b, v211
	v_exp_f32_e32 v151, v151
	v_pk_mul_f32 v[170:171], v[190:191], v[188:189]
	v_add_f32_e32 v0, 1.0, v0
	v_rcp_f32_e32 v188, v0
	v_add_f32_e32 v0, 1.0, v151
	v_lshlrev_b32_e32 v190, 16, v168
	v_rcp_f32_e32 v189, v0
	v_and_b32_e32 v191, 0xffff0000, v168
	v_mul_f32_e32 v0, 0xbfb8aa3b, v190
	v_exp_f32_e32 v0, v0
	v_mul_f32_e32 v151, 0xbfb8aa3b, v191
	v_exp_f32_e32 v151, v151
	v_lshlrev_b32_e32 v222, 16, v169
	v_add_f32_e32 v0, 1.0, v0
	v_rcp_f32_e32 v168, v0
	v_add_f32_e32 v0, 1.0, v151
	v_and_b32_e32 v223, 0xffff0000, v169
	v_mul_f32_e32 v151, 0xbfb8aa3b, v222
	v_exp_f32_e32 v151, v151
	v_mul_f32_e32 v169, 0xbfb8aa3b, v223
	v_exp_f32_e32 v173, v169
	v_rcp_f32_e32 v169, v0
	v_add_f32_e32 v0, 1.0, v151
	v_rcp_f32_e32 v224, v0
	v_add_f32_e32 v0, 1.0, v173
	v_rcp_f32_e32 v225, v0
	v_pk_mul_f32 v[190:191], v[168:169], v[190:191]
	v_pk_mul_f32 v[220:221], v[172:173], v[220:221] op_sel_hi:[0,1]
	v_pk_mul_f32 v[218:219], v[172:173], v[218:219] op_sel_hi:[0,1]
	v_pk_mul_f32 v[168:169], v[224:225], v[222:223]
	v_lshlrev_b32_e32 v222, 16, v158
	v_and_b32_e32 v223, 0xffff0000, v158
	v_mul_f32_e32 v0, 0xbfb8aa3b, v222
	v_pk_mul_f32 v[216:217], v[172:173], v[216:217] op_sel_hi:[0,1]
	v_pk_mul_f32 v[214:215], v[172:173], v[214:215] op_sel_hi:[0,1]
	v_pk_mul_f32 v[208:209], v[172:173], v[208:209] op_sel_hi:[0,1]
	v_pk_mul_f32 v[206:207], v[172:173], v[206:207] op_sel_hi:[0,1]
	v_pk_mul_f32 v[200:201], v[172:173], v[200:201] op_sel_hi:[0,1]
	v_pk_mul_f32 v[198:199], v[172:173], v[198:199] op_sel_hi:[0,1]
	v_exp_f32_e32 v0, v0
	v_pk_fma_f32 v[34:35], v[34:35], v[150:151], v[220:221] op_sel_hi:[1,0,1] neg_lo:[0,0,1] neg_hi:[0,0,1]
	v_pk_fma_f32 v[32:33], v[32:33], v[150:151], v[218:219] op_sel_hi:[1,0,1] neg_lo:[0,0,1] neg_hi:[0,0,1]
	v_pk_fma_f32 v[38:39], v[38:39], v[150:151], v[216:217] op_sel_hi:[1,0,1] neg_lo:[0,0,1] neg_hi:[0,0,1]
	v_pk_fma_f32 v[36:37], v[36:37], v[150:151], v[214:215] op_sel_hi:[1,0,1] neg_lo:[0,0,1] neg_hi:[0,0,1]
	v_pk_fma_f32 v[42:43], v[42:43], v[150:151], v[208:209] op_sel_hi:[1,0,1] neg_lo:[0,0,1] neg_hi:[0,0,1]
	v_pk_fma_f32 v[40:41], v[40:41], v[150:151], v[206:207] op_sel_hi:[1,0,1] neg_lo:[0,0,1] neg_hi:[0,0,1]
	v_pk_fma_f32 v[46:47], v[46:47], v[150:151], v[200:201] op_sel_hi:[1,0,1] neg_lo:[0,0,1] neg_hi:[0,0,1]
	v_pk_fma_f32 v[44:45], v[44:45], v[150:151], v[198:199] op_sel_hi:[1,0,1] neg_lo:[0,0,1] neg_hi:[0,0,1]
	v_mul_f32_e32 v151, 0xbfb8aa3b, v223
	v_exp_f32_e32 v151, v151
	v_add_f32_e32 v0, 1.0, v0
	v_rcp_f32_e32 v198, v0
	v_lshlrev_b32_e32 v200, 16, v159
	v_add_f32_e32 v0, 1.0, v151
	v_rcp_f32_e32 v199, v0
	v_and_b32_e32 v201, 0xffff0000, v159
	v_mul_f32_e32 v0, 0xbfb8aa3b, v200
	v_exp_f32_e32 v0, v0
	v_mul_f32_e32 v151, 0xbfb8aa3b, v201
	v_exp_f32_e32 v151, v151
	v_pk_mul_f32 v[158:159], v[198:199], v[222:223]
	v_add_f32_e32 v0, 1.0, v0
	v_rcp_f32_e32 v198, v0
	v_add_f32_e32 v0, 1.0, v151
	v_lshlrev_b32_e32 v216, 16, v156
	v_rcp_f32_e32 v199, v0
	v_mul_f32_e32 v0, 0xbfb8aa3b, v216
	v_and_b32_e32 v217, 0xffff0000, v156
	v_exp_f32_e32 v0, v0
	v_mul_f32_e32 v151, 0xbfb8aa3b, v217
	v_exp_f32_e32 v151, v151
	v_pk_mul_f32 v[198:199], v[198:199], v[200:201]
	v_add_f32_e32 v0, 1.0, v0
	v_lshlrev_b32_e32 v200, 16, v157
	v_rcp_f32_e32 v156, v0
	v_add_f32_e32 v0, 1.0, v151
	v_and_b32_e32 v201, 0xffff0000, v157
; __device__ __forceinline__ float silu_f(float z) { return z * __builtin_amdgcn_rcpf(1.0f + __builtin_amdgcn_exp2f(-LOG2E * z)); }
; __device__ __forceinline__ float bf_lo(unsigned v) { return __uint_as_float(v << 16); }
; __device__ __forceinline__ float bf_hi(unsigned v) { return __uint_as_float(v & 0xffff0000u); }
; template <int MODE>
; __device__ __forceinline__ void attn_unit(const Params& P, LAS unsigned char* lds, const int b, const int h, const int qb) {
;     ...
;             for (int d = 0; d < 4; ++d)
; #pragma unroll
;                 for (int i = 0; i < 16; ++i) { const float o = O[d][i] * inv1 - lam * xb[((w * 4 + d) * 16 + i) * 64 + lane]; O[d][i] = o; ss += o * o; }
;             ss += __shfl_xor(ss, 32);
;             const float rstd = 0.8f * __builtin_amdgcn_rsqf(ss * (1.0f / 128.0f) + 1e-6f);
; #pragma unroll
;             for (int d = 0; d < 4; ++d)
; #pragma unroll
;                 for (int a = 0; a < 4; ++a) { const int d0 = 32 * d + 8 * a + 4 * hh; const u32x2 z2 = zv[d][a]; const f32x4 g = gv[d][a];
;                     const float o0 = O[d][4 * a] * rstd * g[0] * silu_f(bf_lo(z2.x)), o1 = O[d][4 * a + 1] * rstd * g[1] * silu_f(bf_hi(z2.x));
;                     const float o2 = O[d][4 * a + 2] * rstd * g[2] * silu_f(bf_lo(z2.y)), o3 = O[d][4 * a + 3] * rstd * g[3] * silu_f(bf_hi(z2.y));
	v_mul_f32_e32 v151, 0xbfb8aa3b, v200
	v_exp_f32_e32 v151, v151
	v_mul_f32_e32 v157, 0xbfb8aa3b, v201
	v_exp_f32_e32 v173, v157
	v_rcp_f32_e32 v157, v0
	v_add_f32_e32 v0, 1.0, v151
	v_rcp_f32_e32 v220, v0
	v_add_f32_e32 v0, 1.0, v173
	v_lshlrev_b32_e32 v222, 16, v154
	v_rcp_f32_e32 v221, v0
	v_and_b32_e32 v223, 0xffff0000, v154
	v_mul_f32_e32 v0, 0xbfb8aa3b, v222
	v_exp_f32_e32 v0, v0
	v_mul_f32_e32 v151, 0xbfb8aa3b, v223
	v_exp_f32_e32 v151, v151
	v_pk_mul_f32 v[200:201], v[220:221], v[200:201]
	v_add_f32_e32 v0, 1.0, v0
	v_rcp_f32_e32 v220, v0
	v_add_f32_e32 v0, 1.0, v151
	v_lshlrev_b32_e32 v224, 16, v155
	v_rcp_f32_e32 v221, v0
	v_and_b32_e32 v225, 0xffff0000, v155
	v_mul_f32_e32 v0, 0xbfb8aa3b, v224
	v_exp_f32_e32 v0, v0
	v_mul_f32_e32 v151, 0xbfb8aa3b, v225
	v_exp_f32_e32 v151, v151
	v_pk_mul_f32 v[184:185], v[172:173], v[184:185] op_sel_hi:[0,1]
	v_pk_mul_f32 v[192:193], v[172:173], v[192:193] op_sel_hi:[0,1]
	v_add_f32_e32 v0, 1.0, v0
	v_pk_mul_f32 v[154:155], v[220:221], v[222:223]
	v_rcp_f32_e32 v220, v0
	v_add_f32_e32 v0, 1.0, v151
	v_pk_fma_f32 v[184:185], v[16:17], v[150:151], v[184:185] op_sel_hi:[1,0,1] neg_lo:[0,0,1] neg_hi:[0,0,1]
	v_pk_fma_f32 v[16:17], v[24:25], v[150:151], v[192:193] op_sel_hi:[1,0,1] neg_lo:[0,0,1] neg_hi:[0,0,1]
	v_lshlrev_b32_e32 v24, 16, v152
	v_pk_mul_f32 v[186:187], v[172:173], v[186:187] op_sel_hi:[0,1]
	v_pk_mul_f32 v[196:197], v[172:173], v[196:197] op_sel_hi:[0,1]
	v_rcp_f32_e32 v221, v0
	v_and_b32_e32 v25, 0xffff0000, v152
	v_mul_f32_e32 v0, 0xbfb8aa3b, v24
	v_pk_mul_f32 v[194:195], v[172:173], v[194:195] op_sel_hi:[0,1]
	v_pk_fma_f32 v[172:173], v[18:19], v[150:151], v[186:187] op_sel_hi:[1,0,1] neg_lo:[0,0,1] neg_hi:[0,0,1]
	v_pk_fma_f32 v[18:19], v[22:23], v[150:151], v[196:197] op_sel_hi:[1,0,1] neg_lo:[0,0,1] neg_hi:[0,0,1]
	v_exp_f32_e32 v0, v0
	v_mul_f32_e32 v22, 0xbfb8aa3b, v25
	v_pk_fma_f32 v[20:21], v[20:21], v[150:151], v[194:195] op_sel_hi:[1,0,1] neg_lo:[0,0,1] neg_hi:[0,0,1]
	v_exp_f32_e32 v151, v22
	v_add_f32_e32 v0, 1.0, v0
	v_lshlrev_b32_e32 v152, 16, v153
	v_rcp_f32_e32 v150, v0
	v_add_f32_e32 v0, 1.0, v151
	v_and_b32_e32 v153, 0xffff0000, v153
	v_mul_f32_e32 v151, 0xbfb8aa3b, v152
	v_exp_f32_e32 v186, v151
	v_mul_f32_e32 v151, 0xbfb8aa3b, v153
	v_exp_f32_e32 v187, v151
	v_rcp_f32_e32 v151, v0
	v_add_f32_e32 v0, 1.0, v186
	v_rcp_f32_e32 v186, v0
	v_add_f32_e32 v0, 1.0, v187
	v_lshlrev_b32_e32 v192, 16, v146
	v_rcp_f32_e32 v187, v0
	v_and_b32_e32 v193, 0xffff0000, v146
	v_mul_f32_e32 v0, 0xbfb8aa3b, v192
	v_exp_f32_e32 v0, v0
	v_mul_f32_e32 v146, 0xbfb8aa3b, v193
	v_exp_f32_e32 v146, v146
	v_pk_mul_f32 v[24:25], v[150:151], v[24:25]
	v_add_f32_e32 v0, 1.0, v0
	v_pk_mul_f32 v[150:151], v[186:187], v[152:153]
	v_rcp_f32_e32 v152, v0
	v_add_f32_e32 v0, 1.0, v146
	v_lshlrev_b32_e32 v186, 16, v147
	v_rcp_f32_e32 v153, v0
	v_and_b32_e32 v187, 0xffff0000, v147
	v_mul_f32_e32 v0, 0xbfb8aa3b, v186
	v_exp_f32_e32 v0, v0
	v_mul_f32_e32 v146, 0xbfb8aa3b, v187
	v_exp_f32_e32 v194, v146
	v_pk_mul_f32 v[146:147], v[152:153], v[192:193]
	v_add_f32_e32 v0, 1.0, v0
	v_rcp_f32_e32 v152, v0
	v_add_f32_e32 v0, 1.0, v194
	v_lshlrev_b32_e32 v192, 16, v144
	v_rcp_f32_e32 v153, v0
	v_and_b32_e32 v193, 0xffff0000, v144
	v_mul_f32_e32 v0, 0xbfb8aa3b, v192
	v_exp_f32_e32 v0, v0
	v_mul_f32_e32 v144, 0xbfb8aa3b, v193
	v_exp_f32_e32 v144, v144
	v_pk_mul_f32 v[152:153], v[152:153], v[186:187]
	v_add_f32_e32 v0, 1.0, v0
	v_rcp_f32_e32 v186, v0
	v_add_f32_e32 v0, 1.0, v144
	v_lshlrev_b32_e32 v194, 16, v145
	v_rcp_f32_e32 v187, v0
	v_and_b32_e32 v195, 0xffff0000, v145
	v_mul_f32_e32 v0, 0xbfb8aa3b, v194
	v_exp_f32_e32 v0, v0
	v_mul_f32_e32 v144, 0xbfb8aa3b, v195
	v_exp_f32_e32 v196, v144
	v_pk_mul_f32 v[144:145], v[186:187], v[192:193]
	v_add_f32_e32 v0, 1.0, v0
	v_rcp_f32_e32 v186, v0
	v_add_f32_e32 v0, 1.0, v196
	v_lshlrev_b32_e32 v192, 16, v142
	v_rcp_f32_e32 v187, v0
	v_and_b32_e32 v193, 0xffff0000, v142
	v_mul_f32_e32 v0, 0xbfb8aa3b, v192
	v_exp_f32_e32 v0, v0
	v_mul_f32_e32 v142, 0xbfb8aa3b, v193
	v_exp_f32_e32 v142, v142
	v_pk_mul_f32 v[186:187], v[186:187], v[194:195]
	v_add_f32_e32 v0, 1.0, v0
	v_rcp_f32_e32 v194, v0
	v_add_f32_e32 v0, 1.0, v142
	v_lshlrev_b32_e32 v196, 16, v143
	v_rcp_f32_e32 v195, v0
	v_and_b32_e32 v197, 0xffff0000, v143
	v_mul_f32_e32 v0, 0xbfb8aa3b, v196
	v_exp_f32_e32 v0, v0
	v_mul_f32_e32 v142, 0xbfb8aa3b, v197
	v_pk_mul_f32 v[22:23], v[220:221], v[224:225]
	v_exp_f32_e32 v220, v142
	v_add_f32_e32 v0, 1.0, v0
	v_pk_mul_f32 v[142:143], v[194:195], v[192:193]
	v_rcp_f32_e32 v192, v0
	v_add_f32_e32 v0, 1.0, v220
	v_lshlrev_b32_e32 v194, 16, v140
	v_rcp_f32_e32 v193, v0
	v_and_b32_e32 v195, 0xffff0000, v140
	v_mul_f32_e32 v0, 0xbfb8aa3b, v194
	v_exp_f32_e32 v0, v0
	v_mul_f32_e32 v140, 0xbfb8aa3b, v195
	v_exp_f32_e32 v140, v140
	v_pk_mul_f32 v[192:193], v[192:193], v[196:197]
	v_add_f32_e32 v0, 1.0, v0
	v_rcp_f32_e32 v196, v0
	v_add_f32_e32 v0, 1.0, v140
	v_lshlrev_b32_e32 v220, 16, v141
	v_rcp_f32_e32 v197, v0
	v_and_b32_e32 v221, 0xffff0000, v141
	v_mul_f32_e32 v0, 0xbfb8aa3b, v220
	v_exp_f32_e32 v0, v0
	v_mul_f32_e32 v140, 0xbfb8aa3b, v221
	v_exp_f32_e32 v224, v140
	v_pk_mul_f32 v[140:141], v[196:197], v[194:195]
	v_add_f32_e32 v0, 1.0, v0
	v_rcp_f32_e32 v194, v0
	v_add_f32_e32 v0, 1.0, v224
	v_lshlrev_b32_e32 v196, 16, v138
	v_rcp_f32_e32 v195, v0
	v_and_b32_e32 v197, 0xffff0000, v138
	v_mul_f32_e32 v0, 0xbfb8aa3b, v196
	v_exp_f32_e32 v0, v0
	v_mul_f32_e32 v138, 0xbfb8aa3b, v197
	v_exp_f32_e32 v224, v138
	v_pk_mul_f32 v[194:195], v[194:195], v[220:221]
	v_lshlrev_b32_e32 v220, 16, v139
	v_add_f32_e32 v0, 1.0, v0
	v_and_b32_e32 v221, 0xffff0000, v139
	v_mul_f32_e32 v139, 0xbfb8aa3b, v220
; template <int MODE>
; __device__ __forceinline__ void attn_unit(const Params& P, LAS unsigned char* lds, const int b, const int h, const int qb) {
;     ...
;             for (int d = 0; d < 4; ++d)
; #pragma unroll
;                 for (int i = 0; i < 16; ++i) { const float o = O[d][i] * inv1 - lam * xb[((w * 4 + d) * 16 + i) * 64 + lane]; O[d][i] = o; ss += o * o; }
;             ss += __shfl_xor(ss, 32);
;             const float rstd = 0.8f * __builtin_amdgcn_rsqf(ss * (1.0f / 128.0f) + 1e-6f);
	v_rcp_f32_e32 v138, v0
	v_add_f32_e32 v0, 1.0, v224
	v_exp_f32_e32 v224, v139
	v_mul_f32_e32 v139, 0xbfb8aa3b, v221
	v_exp_f32_e32 v225, v139
	v_lshl_add_u64 v[74:75], v[226:227], 0, v[148:149]
	v_lshlrev_b32_e32 v226, 16, v136
	v_rcp_f32_e32 v139, v0
	v_add_f32_e32 v0, 1.0, v224
	v_and_b32_e32 v227, 0xffff0000, v136
	v_mul_f32_e32 v136, 0xbfb8aa3b, v226
	v_rcp_f32_e32 v224, v0
	v_add_f32_e32 v0, 1.0, v225
	v_exp_f32_e32 v136, v136
	v_mul_f32_e32 v225, 0xbfb8aa3b, v227
	v_exp_f32_e32 v229, v225
	v_rcp_f32_e32 v225, v0
	v_add_f32_e32 v0, 1.0, v136
	v_pk_mul_f32 v[148:149], v[166:167], v[166:167]
	v_rcp_f32_e32 v236, v0
	v_add_f32_e32 v0, 1.0, v229
	v_pk_mul_f32 v[182:183], v[164:165], v[164:165]
	v_rcp_f32_e32 v237, v0
	v_add_f32_e32 v0, v148, v149
	v_add_f32_e32 v0, v0, v182
	v_pk_mul_f32 v[204:205], v[162:163], v[162:163]
	v_add_f32_e32 v0, v0, v183
	v_add_f32_e32 v0, v0, v204
	v_pk_mul_f32 v[202:203], v[160:161], v[160:161]
	v_add_f32_e32 v0, v0, v205
	v_add_f32_e32 v0, v0, v202
	v_pk_mul_f32 v[212:213], v[70:71], v[70:71]
	v_add_f32_e32 v0, v0, v203
	v_add_f32_e32 v0, v0, v212
	v_pk_mul_f32 v[188:189], v[188:189], v[210:211]
	v_pk_mul_f32 v[210:211], v[68:69], v[68:69]
	v_add_f32_e32 v0, v0, v213
	v_add_f32_e32 v0, v0, v210
	v_pk_mul_f32 v[214:215], v[66:67], v[66:67]
	v_add_f32_e32 v0, v0, v211
	v_add_f32_e32 v0, v0, v214
	v_pk_mul_f32 v[206:207], v[64:65], v[64:65]
	v_add_f32_e32 v0, v0, v215
	v_add_f32_e32 v0, v0, v206
	v_pk_mul_f32 v[218:219], v[48:49], v[48:49]
	v_add_f32_e32 v0, v0, v207
	v_add_f32_e32 v0, v0, v218
	v_pk_mul_f32 v[208:209], v[50:51], v[50:51]
	v_add_f32_e32 v0, v0, v219
	v_add_f32_e32 v0, v0, v208
	v_pk_mul_f32 v[222:223], v[52:53], v[52:53]
	v_add_f32_e32 v0, v0, v209
	v_add_f32_e32 v0, v0, v222
	v_pk_mul_f32 v[156:157], v[156:157], v[216:217]
	v_pk_mul_f32 v[216:217], v[54:55], v[54:55]
	v_add_f32_e32 v0, v0, v223
	v_add_f32_e32 v0, v0, v216
	v_pk_mul_f32 v[196:197], v[138:139], v[196:197]
	v_pk_mul_f32 v[138:139], v[236:237], v[226:227]
	v_pk_mul_f32 v[226:227], v[56:57], v[56:57]
	v_add_f32_e32 v0, v0, v217
	v_add_f32_e32 v0, v0, v226
	v_pk_mul_f32 v[238:239], v[58:59], v[58:59]
	v_add_f32_e32 v0, v0, v227
	v_add_f32_e32 v0, v0, v238
	v_pk_mul_f32 v[182:183], v[60:61], v[60:61]
	v_add_f32_e32 v0, v0, v239
	v_add_f32_e32 v0, v0, v182
	v_pk_mul_f32 v[148:149], v[62:63], v[62:63]
	v_add_f32_e32 v0, v0, v183
	v_add_f32_e32 v0, v0, v148
	v_pk_mul_f32 v[202:203], v[32:33], v[32:33]
	v_add_f32_e32 v0, v0, v149
	v_add_f32_e32 v0, v0, v202
	v_pk_mul_f32 v[204:205], v[34:35], v[34:35]
	v_add_f32_e32 v0, v0, v203
	v_add_f32_e32 v0, v0, v204
	v_pk_mul_f32 v[210:211], v[36:37], v[36:37]
	v_add_f32_e32 v0, v0, v205
	v_add_f32_e32 v0, v0, v210
	v_pk_mul_f32 v[212:213], v[38:39], v[38:39]
	v_add_f32_e32 v0, v0, v211
	v_add_f32_e32 v0, v0, v212
	v_lshlrev_b32_e32 v136, 16, v137
	v_and_b32_e32 v137, 0xffff0000, v137
	v_pk_mul_f32 v[206:207], v[40:41], v[40:41]
	v_add_f32_e32 v0, v0, v213
	v_mul_f32_e32 v218, 0xbfb8aa3b, v136
	v_mul_f32_e32 v219, 0xbfb8aa3b, v137
	v_add_f32_e32 v0, v0, v206
	v_pk_mul_f32 v[214:215], v[42:43], v[42:43]
	v_exp_f32_e32 v218, v218
	v_exp_f32_e32 v219, v219
	v_add_f32_e32 v0, v0, v207
	v_add_f32_e32 v0, v0, v214
	v_pk_mul_f32 v[222:223], v[44:45], v[44:45]
	v_add_f32_e32 v0, v0, v215
	v_add_f32_e32 v0, v0, v222
	v_add_f32_e32 v208, 1.0, v218
	v_add_f32_e32 v209, 1.0, v219
	v_pk_mul_f32 v[218:219], v[46:47], v[46:47]
	v_add_f32_e32 v0, v0, v223
	v_add_f32_e32 v0, v0, v218
	v_pk_mul_f32 v[236:237], v[184:185], v[184:185]
	v_add_f32_e32 v0, v0, v219
	v_add_f32_e32 v0, v0, v236
	v_pk_mul_f32 v[226:227], v[172:173], v[172:173]
	v_add_f32_e32 v0, v0, v237
	v_add_f32_e32 v0, v0, v226
	v_pk_mul_f32 v[148:149], v[20:21], v[20:21]
	v_add_f32_e32 v0, v0, v227
	v_pk_mul_f32 v[220:221], v[224:225], v[220:221]
	v_lshlrev_b32_e32 v224, 16, v134
	v_and_b32_e32 v225, 0xffff0000, v134
	v_lshlrev_b32_e32 v134, 16, v135
	v_add_f32_e32 v0, v0, v148
	v_and_b32_e32 v135, 0xffff0000, v135
	v_pk_mul_f32 v[182:183], v[18:19], v[18:19]
	v_mul_f32_e32 v202, 0xbfb8aa3b, v134
	v_add_f32_e32 v0, v0, v149
	v_exp_f32_e32 v229, v202
	v_mul_f32_e32 v202, 0xbfb8aa3b, v135
	v_add_f32_e32 v0, v0, v182
	v_exp_f32_e32 v238, v202
	v_pk_mul_f32 v[202:203], v[16:17], v[16:17]
	v_add_f32_e32 v0, v0, v183
	v_add_f32_e32 v0, v0, v202
	v_rcp_f32_e32 v79, v79
	v_pk_mul_f32 v[174:175], v[72:73], v[72:73]
	v_add_f32_e32 v0, v0, v203
	v_add_f32_e32 v0, v0, v174
	v_pk_mul_f32 v[176:177], v[28:29], v[28:29]
	v_add_f32_e32 v0, v0, v175
	v_add_f32_e32 v0, v0, v176
	v_pk_mul_f32 v[78:79], v[78:79], v[180:181]
	v_pk_mul_f32 v[180:181], v[26:27], v[26:27]
	v_add_f32_e32 v0, v0, v177
	v_add_f32_e32 v0, v0, v180
	v_add_f32_e32 v0, v0, v181
	ds_bpermute_b32 v174, v228, v0
	v_mul_f32_e32 v216, 0xbfb8aa3b, v224
	v_mul_f32_e32 v217, 0xbfb8aa3b, v225
	v_exp_f32_e32 v216, v216
	v_exp_f32_e32 v217, v217
	s_waitcnt lgkmcnt(0)
; __device__ __forceinline__ float silu_f(float z) { return z * __builtin_amdgcn_rcpf(1.0f + __builtin_amdgcn_exp2f(-LOG2E * z)); }
; __device__ __forceinline__ float bf_lo(unsigned v) { return __uint_as_float(v << 16); }
; __device__ __forceinline__ float bf_hi(unsigned v) { return __uint_as_float(v & 0xffff0000u); }
; template <int MODE>
; __device__ __forceinline__ void attn_unit(const Params& P, LAS unsigned char* lds, const int b, const int h, const int qb) {
;     ...
;             const float rstd = 0.8f * __builtin_amdgcn_rsqf(ss * (1.0f / 128.0f) + 1e-6f);
; #pragma unroll
;             for (int d = 0; d < 4; ++d)
; #pragma unroll
;                 for (int a = 0; a < 4; ++a) { const int d0 = 32 * d + 8 * a + 4 * hh; const u32x2 z2 = zv[d][a]; const f32x4 g = gv[d][a];
;                     const float o0 = O[d][4 * a] * rstd * g[0] * silu_f(bf_lo(z2.x)), o1 = O[d][4 * a + 1] * rstd * g[1] * silu_f(bf_hi(z2.x));
;                     const float o2 = O[d][4 * a + 2] * rstd * g[2] * silu_f(bf_lo(z2.y)), o3 = O[d][4 * a + 3] * rstd * g[3] * silu_f(bf_hi(z2.y));
;                     u32x2 ov; ov.x = cvt_pk_bf16(o0, o1); ov.y = cvt_pk_bf16(o2, o3); *(u32x2*)(mix + d0) = ov; }
	v_add_f32_e32 v0, v0, v174
	v_fmamk_f32 v0, v0, 0x3c000000, v230
	v_rsq_f32_e32 v0, v0
	v_add_f32_e32 v216, 1.0, v216
	v_add_f32_e32 v217, 1.0, v217
	v_rcp_f32_e32 v216, v216
	v_rcp_f32_e32 v217, v217
	v_add_f32_e32 v148, 1.0, v229
	v_add_f32_e32 v149, 1.0, v238
	v_rcp_f32_e32 v148, v148
	v_rcp_f32_e32 v149, v149
	v_mul_f32_e32 v0, 0x3f4ccccd, v0
	v_pk_mul_f32 v[20:21], v[20:21], v[0:1] op_sel_hi:[1,0]
	v_pk_mul_f32 v[174:175], v[216:217], v[224:225]
	v_pk_mul_f32 v[10:11], v[10:11], v[20:21]
	v_pk_mul_f32 v[18:19], v[18:19], v[0:1] op_sel_hi:[1,0]
	v_pk_mul_f32 v[134:135], v[148:149], v[134:135]
	v_pk_mul_f32 v[48:49], v[48:49], v[0:1] op_sel_hi:[1,0]
	v_pk_mul_f32 v[50:51], v[50:51], v[0:1] op_sel_hi:[1,0]
	v_pk_mul_f32 v[10:11], v[174:175], v[10:11]
	v_pk_mul_f32 v[12:13], v[12:13], v[18:19]
	v_lshlrev_b32_e32 v18, 16, v132
	v_pk_mul_f32 v[48:49], v[112:113], v[48:49]
	v_pk_mul_f32 v[50:51], v[114:115], v[50:51]
	v_pk_mul_f32 v[12:13], v[134:135], v[12:13]
	v_cvt_pk_bf16_f32 v10, v10, v11
	v_mul_f32_e32 v11, 0xbfb8aa3b, v18
	v_lshl_add_u64 v[30:31], v[74:75], 0, s[0:1]
	v_pk_mul_f32 v[48:49], v[156:157], v[48:49]
	v_pk_mul_f32 v[50:51], v[200:201], v[50:51]
	v_exp_f32_e32 v20, v11
	v_cvt_pk_bf16_f32 v11, v12, v13
	v_and_b32_e32 v19, 0xffff0000, v132
	v_cvt_pk_bf16_f32 v48, v48, v49
	v_cvt_pk_bf16_f32 v49, v50, v51
	global_store_dwordx2 v[30:31], v[10:11], off offset:208
	v_mul_f32_e32 v11, 0xbfb8aa3b, v19
	v_pk_mul_f32 v[12:13], v[16:17], v[0:1] op_sel_hi:[1,0]
	global_store_dwordx2 v[30:31], v[48:49], off offset:64
	v_pk_mul_f32 v[48:49], v[52:53], v[0:1] op_sel_hi:[1,0]
	v_pk_mul_f32 v[50:51], v[54:55], v[0:1] op_sel_hi:[1,0]
	v_exp_f32_e32 v11, v11
	v_pk_mul_f32 v[6:7], v[6:7], v[12:13]
	v_lshlrev_b32_e32 v12, 16, v133
	v_and_b32_e32 v13, 0xffff0000, v133
	v_pk_mul_f32 v[48:49], v[108:109], v[48:49]
	v_pk_mul_f32 v[50:51], v[110:111], v[50:51]
	v_mul_f32_e32 v16, 0xbfb8aa3b, v12
	v_mul_f32_e32 v17, 0xbfb8aa3b, v13
	v_pk_mul_f32 v[48:49], v[154:155], v[48:49]
	v_pk_mul_f32 v[22:23], v[22:23], v[50:51]
	v_exp_f32_e32 v16, v16
	v_exp_f32_e32 v17, v17
	v_cvt_pk_bf16_f32 v48, v48, v49
	v_cvt_pk_bf16_f32 v49, v22, v23
	v_pk_mul_f32 v[22:23], v[56:57], v[0:1] op_sel_hi:[1,0]
	v_add_f32_e32 v10, 1.0, v20
	v_pk_mul_f32 v[22:23], v[104:105], v[22:23]
	v_add_f32_e32 v11, 1.0, v11
	v_pk_mul_f32 v[22:23], v[24:25], v[22:23]
	v_pk_mul_f32 v[24:25], v[58:59], v[0:1] op_sel_hi:[1,0]
	v_rcp_f32_e32 v10, v10
	v_rcp_f32_e32 v11, v11
	v_pk_mul_f32 v[24:25], v[106:107], v[24:25]
	v_add_f32_e32 v16, 1.0, v16
	v_add_f32_e32 v17, 1.0, v17
	v_pk_mul_f32 v[24:25], v[150:151], v[24:25]
	v_rcp_f32_e32 v16, v16
	v_rcp_f32_e32 v17, v17
	v_cvt_pk_bf16_f32 v22, v22, v23
	v_cvt_pk_bf16_f32 v23, v24, v25
	global_store_dwordx2 v[30:31], v[22:23], off offset:96
	v_pk_mul_f32 v[22:23], v[60:61], v[0:1] op_sel_hi:[1,0]
	v_pk_mul_f32 v[24:25], v[62:63], v[0:1] op_sel_hi:[1,0]
	v_pk_mul_f32 v[10:11], v[10:11], v[18:19]
	v_pk_mul_f32 v[22:23], v[100:101], v[22:23]
	v_pk_mul_f32 v[24:25], v[102:103], v[24:25]
	v_pk_mul_f32 v[6:7], v[10:11], v[6:7]
	v_pk_mul_f32 v[10:11], v[72:73], v[0:1] op_sel_hi:[1,0]
	v_pk_mul_f32 v[22:23], v[146:147], v[22:23]
	v_pk_mul_f32 v[24:25], v[152:153], v[24:25]
	v_pk_mul_f32 v[8:9], v[8:9], v[10:11]
	v_pk_mul_f32 v[10:11], v[16:17], v[12:13]
	v_cvt_pk_bf16_f32 v22, v22, v23
	v_cvt_pk_bf16_f32 v23, v24, v25
	v_pk_mul_f32 v[8:9], v[10:11], v[8:9]
	v_lshlrev_b32_e32 v10, 16, v14
	global_store_dwordx2 v[30:31], v[22:23], off offset:112
	v_pk_mul_f32 v[22:23], v[32:33], v[0:1] op_sel_hi:[1,0]
	v_pk_mul_f32 v[24:25], v[34:35], v[0:1] op_sel_hi:[1,0]
	v_cvt_pk_bf16_f32 v6, v6, v7
	v_mul_f32_e32 v7, 0xbfb8aa3b, v10
	v_pk_mul_f32 v[22:23], v[96:97], v[22:23]
	v_pk_mul_f32 v[24:25], v[98:99], v[24:25]
	v_exp_f32_e32 v12, v7
	v_cvt_pk_bf16_f32 v7, v8, v9
	v_and_b32_e32 v11, 0xffff0000, v14
	v_pk_mul_f32 v[22:23], v[144:145], v[22:23]
	v_pk_mul_f32 v[24:25], v[186:187], v[24:25]
	global_store_dwordx2 v[30:31], v[6:7], off offset:224
	v_mul_f32_e32 v7, 0xbfb8aa3b, v11
	v_cvt_pk_bf16_f32 v22, v22, v23
	v_cvt_pk_bf16_f32 v23, v24, v25
	v_exp_f32_e32 v7, v7
	global_store_dwordx2 v[30:31], v[22:23], off offset:128
	v_pk_mul_f32 v[22:23], v[36:37], v[0:1] op_sel_hi:[1,0]
	v_pk_mul_f32 v[24:25], v[38:39], v[0:1] op_sel_hi:[1,0]
; __device__ __forceinline__ float silu_f(float z) { return z * __builtin_amdgcn_rcpf(1.0f + __builtin_amdgcn_exp2f(-LOG2E * z)); }
; __device__ __forceinline__ float bf_lo(unsigned v) { return __uint_as_float(v << 16); }
; __device__ __forceinline__ float bf_hi(unsigned v) { return __uint_as_float(v & 0xffff0000u); }
; template <int MODE>
; __device__ __forceinline__ void attn_unit(const Params& P, LAS unsigned char* lds, const int b, const int h, const int qb) {
;     ...
;             for (int d = 0; d < 4; ++d)
; #pragma unroll
;                 for (int a = 0; a < 4; ++a) { const int d0 = 32 * d + 8 * a + 4 * hh; const u32x2 z2 = zv[d][a]; const f32x4 g = gv[d][a];
;                     const float o0 = O[d][4 * a] * rstd * g[0] * silu_f(bf_lo(z2.x)), o1 = O[d][4 * a + 1] * rstd * g[1] * silu_f(bf_hi(z2.x));
;                     const float o2 = O[d][4 * a + 2] * rstd * g[2] * silu_f(bf_lo(z2.y)), o3 = O[d][4 * a + 3] * rstd * g[3] * silu_f(bf_hi(z2.y));
;                     u32x2 ov; ov.x = cvt_pk_bf16(o0, o1); ov.y = cvt_pk_bf16(o2, o3); *(u32x2*)(mix + d0) = ov; }
	v_pk_mul_f32 v[22:23], v[92:93], v[22:23]
	v_pk_mul_f32 v[24:25], v[94:95], v[24:25]
	v_pk_mul_f32 v[8:9], v[28:29], v[0:1] op_sel_hi:[1,0]
	v_pk_mul_f32 v[22:23], v[142:143], v[22:23]
	v_pk_mul_f32 v[24:25], v[192:193], v[24:25]
	v_pk_mul_f32 v[2:3], v[2:3], v[8:9]
	v_lshlrev_b32_e32 v8, 16, v15
	v_and_b32_e32 v9, 0xffff0000, v15
	v_cvt_pk_bf16_f32 v22, v22, v23
	v_cvt_pk_bf16_f32 v23, v24, v25
	v_add_f32_e32 v6, 1.0, v12
	v_add_f32_e32 v7, 1.0, v7
	v_mul_f32_e32 v12, 0xbfb8aa3b, v8
	v_mul_f32_e32 v13, 0xbfb8aa3b, v9
	global_store_dwordx2 v[30:31], v[22:23], off offset:144
	v_pk_mul_f32 v[22:23], v[40:41], v[0:1] op_sel_hi:[1,0]
	v_pk_mul_f32 v[24:25], v[42:43], v[0:1] op_sel_hi:[1,0]
	v_rcp_f32_e32 v6, v6
	v_rcp_f32_e32 v7, v7
	v_exp_f32_e32 v12, v12
	v_exp_f32_e32 v13, v13
	v_pk_mul_f32 v[22:23], v[88:89], v[22:23]
	v_pk_mul_f32 v[24:25], v[90:91], v[24:25]
	v_pk_mul_f32 v[148:149], v[166:167], v[0:1] op_sel_hi:[1,0]
	v_pk_mul_f32 v[22:23], v[140:141], v[22:23]
	v_pk_mul_f32 v[24:25], v[194:195], v[24:25]
	v_pk_mul_f32 v[128:129], v[128:129], v[148:149]
	v_cvt_pk_bf16_f32 v22, v22, v23
	v_cvt_pk_bf16_f32 v23, v24, v25
	v_pk_mul_f32 v[78:79], v[78:79], v[128:129]
	v_pk_mul_f32 v[128:129], v[164:165], v[0:1] op_sel_hi:[1,0]
	global_store_dwordx2 v[30:31], v[22:23], off offset:160
	v_pk_mul_f32 v[22:23], v[44:45], v[0:1] op_sel_hi:[1,0]
	v_pk_mul_f32 v[24:25], v[46:47], v[0:1] op_sel_hi:[1,0]
	v_pk_mul_f32 v[6:7], v[6:7], v[10:11]
	v_add_f32_e32 v10, 1.0, v12
	v_add_f32_e32 v11, 1.0, v13
	v_rcp_f32_e32 v208, v208
	v_rcp_f32_e32 v209, v209
	v_pk_mul_f32 v[128:129], v[130:131], v[128:129]
	s_mov_b32 s0, 0x4324000
	v_pk_mul_f32 v[22:23], v[84:85], v[22:23]
	v_pk_mul_f32 v[24:25], v[86:87], v[24:25]
	v_rcp_f32_e32 v10, v10
	v_rcp_f32_e32 v11, v11
	v_pk_mul_f32 v[76:77], v[76:77], v[128:129]
	v_add_co_u32_e32 v74, vcc, s0, v74
	v_pk_mul_f32 v[22:23], v[196:197], v[22:23]
	v_pk_mul_f32 v[24:25], v[220:221], v[24:25]
	v_cvt_pk_bf16_f32 v78, v78, v79
	v_cvt_pk_bf16_f32 v79, v76, v77
	v_addc_co_u32_e32 v75, vcc, 0, v75, vcc
	v_cvt_pk_bf16_f32 v22, v22, v23
	v_cvt_pk_bf16_f32 v23, v24, v25
	global_store_dwordx2 v[74:75], v[78:79], off offset:2048
	v_pk_mul_f32 v[74:75], v[162:163], v[0:1] op_sel_hi:[1,0]
	v_pk_mul_f32 v[76:77], v[160:161], v[0:1] op_sel_hi:[1,0]
	v_pk_mul_f32 v[70:71], v[70:71], v[0:1] op_sel_hi:[1,0]
	v_pk_mul_f32 v[68:69], v[68:69], v[0:1] op_sel_hi:[1,0]
	v_pk_mul_f32 v[66:67], v[66:67], v[0:1] op_sel_hi:[1,0]
	v_pk_mul_f32 v[64:65], v[64:65], v[0:1] op_sel_hi:[1,0]
	global_store_dwordx2 v[30:31], v[22:23], off offset:176
	v_pk_mul_f32 v[22:23], v[184:185], v[0:1] op_sel_hi:[1,0]
	v_pk_mul_f32 v[24:25], v[172:173], v[0:1] op_sel_hi:[1,0]
	v_pk_mul_f32 v[2:3], v[6:7], v[2:3]
	v_pk_mul_f32 v[6:7], v[26:27], v[0:1] op_sel_hi:[1,0]
	v_pk_mul_f32 v[136:137], v[208:209], v[136:137]
	v_pk_mul_f32 v[74:75], v[124:125], v[74:75]
	v_pk_mul_f32 v[76:77], v[126:127], v[76:77]
	v_pk_mul_f32 v[70:71], v[120:121], v[70:71]
	v_pk_mul_f32 v[68:69], v[122:123], v[68:69]
	v_pk_mul_f32 v[66:67], v[116:117], v[66:67]
	v_pk_mul_f32 v[64:65], v[118:119], v[64:65]
	v_pk_mul_f32 v[22:23], v[80:81], v[22:23]
	v_pk_mul_f32 v[24:25], v[82:83], v[24:25]
	v_pk_mul_f32 v[4:5], v[4:5], v[6:7]
	v_pk_mul_f32 v[6:7], v[10:11], v[8:9]
	v_pk_mul_f32 v[74:75], v[170:171], v[74:75]
	v_pk_mul_f32 v[76:77], v[188:189], v[76:77]
	v_pk_mul_f32 v[70:71], v[190:191], v[70:71]
	v_pk_mul_f32 v[68:69], v[168:169], v[68:69]
	v_pk_mul_f32 v[66:67], v[158:159], v[66:67]
	v_pk_mul_f32 v[64:65], v[198:199], v[64:65]
	v_pk_mul_f32 v[22:23], v[138:139], v[22:23]
	v_pk_mul_f32 v[24:25], v[136:137], v[24:25]
	v_pk_mul_f32 v[4:5], v[6:7], v[4:5]
	v_cvt_pk_bf16_f32 v74, v74, v75
	v_cvt_pk_bf16_f32 v75, v76, v77
	v_cvt_pk_bf16_f32 v70, v70, v71
	v_cvt_pk_bf16_f32 v71, v68, v69
	v_cvt_pk_bf16_f32 v66, v66, v67
	v_cvt_pk_bf16_f32 v67, v64, v65
	v_cvt_pk_bf16_f32 v22, v22, v23
	v_cvt_pk_bf16_f32 v23, v24, v25
	v_cvt_pk_bf16_f32 v2, v2, v3
	v_cvt_pk_bf16_f32 v3, v4, v5
	global_store_dwordx2 v[30:31], v[74:75], off offset:16
	global_store_dwordx2 v[30:31], v[70:71], off offset:32
	global_store_dwordx2 v[30:31], v[66:67], off offset:48
	global_store_dwordx2 v[30:31], v[48:49], off offset:80
	global_store_dwordx2 v[30:31], v[22:23], off offset:192
	global_store_dwordx2 v[30:31], v[2:3], off offset:240
